# attention loop VALU diet: K/V LDS-DMAs use SGPR base + 32-bit lane offset (9 64-bit VALU adds per 2 steps removed, pointers bumped on SALU), no-op +0 adds dropped
# speedup vs baseline: 1.0080x; 1.0080x over previous
; #define WAIT_BAR(N) asm volatile("s_waitcnt vmcnt(" #N ") lgkmcnt(0)\n\ts_barrier":::"memory")
;   #define DMA_K(t,slot) glds16(ksrc+(long)(t)*KVBLK*DM,(unsigned)__builtin_amdgcn_readfirstlane(kdst+(slot)))
;   #define DMA_V(t,slot) do{ glds16(vsrc+(long)(t)*KVBLK*DM,(unsigned)__builtin_amdgcn_readfirstlane(vdst+2*(slot))); glds16(vsrc+(long)(t)*KVBLK*DM+64,(unsigned)__builtin_amdgcn_readfirstlane(vdst+2*(slot)+8192)); }while(0)
;   #define CMASK(P0,P1,t) do{int jb_=(t)-(NT-4); if(jb_>=0)cmask(P0,P1,jb_,qrel,hi);}while(0)
;   #define ROT() do{sl_prev=sl_cur;sl_cur=sl_next;sl_next=(sl_next==(NSLOT-1)*SLOTB)?0:sl_next+SLOTB;}while(0)
;   #define CMASK(P0,P1,t) do{}while(0)
;   #define CMASK(P0,P1,t) do{int jb_=(t)-(NT-4); if(jb_>=0)cmask(P0,P1,jb_,qrel,hi);}while(0)
; template<int DUMMY> __device__ __forceinline__ void attn_pass2(const bf16*Qh,const bf16*__restrict__ Kh,const bf16*__restrict__ Vh,const int q0,char*shm,f32x16 (&o)[4]){
;     ...
;   const lds_cptr shm3=(lds_cptr)shm; const lds_cptr kp0=shm3+L2_K+hi*1024+r32*16; const lds_cptr vp0=shm3+L2_V+((lane>>4)&1)*32+(lane&3)*8+(4*hi+((lane&15)>>2))*64;
;   const int NT=(q0+QB)/KVBLK;
;   DMA_K(0,0);DMA_V(0,0);DMA_K(1,SLOTB);
;   bf16x8 qr[4];
;   #pragma unroll
;   for(int d0=0;d0<4;++d0)qr[d0]=*reinterpret_cast<const bf16x8*>(&Qw[(long)r32*DM+d0*16+hi*8]);
;   float l_reg=0.f;o[0]=f32x16{};o[1]=f32x16{};o[2]=f32x16{};o[3]=f32x16{};
;   const f32x16 zero16=f32x16{};
;   const int qrel=wid*QBLK+r32;
;     ...
;   f32x16 pA0,pA1,pB0,pB1;
;   int sl_prev=0,sl_cur=0,sl_next=SLOTB;
;     ...
;   DMA_K(2,2*SLOTB);
;   WAIT_BAR(4);
;   qkt(pA0,pA1,Kbase,qr,zero16,r32,hi);CMASK(pA0,pA1,0);
;   _Pragma("unroll") for(int r=0;r<16;++r){pA0[r]=__builtin_amdgcn_exp2f(pA0[r]);pA1[r]=__builtin_amdgcn_exp2f(pA1[r]);}
;   WAIT_BAR(0);
;   DMA_K(3,0);DMA_V(1,SLOTB);
;   ROT();
;   kload8(kf,kp0+sl_cur);
;   WAIT_BAR(3);
;   s16x4 vlo[8],vhi[8]; u32x4 pw0,pw1,pw2,pw3;
.LBB0_302:
	s_waitcnt vmcnt(0) lgkmcnt(0)
	s_barrier
	s_ashr_i32 s25, s14, 6
	s_nop 7
	v_exp_f32_e32 v96, v0
	v_exp_f32_e32 v97, v1
	v_lshl_add_u64 v[0:1], v[208:209], 0, s[42:43]
	s_mov_b32 s14, m0
	s_mov_b32 m0, s20
	s_nop 0
	global_load_lds_dwordx4 v[0:1], off
	s_mov_b32 m0, s14
	s_mov_b64 s[14:15], 0x60000
	s_cmp_lg_u32 0, -1
	v_lshl_add_u64 v[0:1], v[32:33], 0, s[14:15]
	s_cselect_b32 s14, 0, 0
	s_add_i32 s11, s14, s11
	s_add_i32 s14, s11, 0xa000
	s_mov_b32 s15, m0
	s_mov_b32 m0, s14
	s_nop 0
	global_load_lds_dwordx4 v[0:1], off
	s_mov_b32 m0, s15
	s_mov_b64 s[14:15], 0x60080
	v_lshl_add_u64 v[0:1], v[32:33], 0, s[14:15]
	s_add_i32 s11, s11, 0xc000
	s_mov_b32 s14, m0
	s_mov_b32 m0, s11
	s_nop 0
	global_load_lds_dwordx4 v[0:1], off
	s_mov_b32 m0, s14
	ds_read_b128 v[204:207], v241 offset:8192
	ds_read_b128 v[200:203], v241 offset:8704
	ds_read_b128 v[196:199], v241 offset:10240
	ds_read_b128 v[192:195], v241 offset:10752
	ds_read_b128 v[188:191], v241 offset:12288
	ds_read_b128 v[184:187], v241 offset:12800
	ds_read_b128 v[180:183], v241 offset:14336
	ds_read_b128 v[176:179], v241 offset:14848
	v_lshlrev_b32_e32 v36, 1, v34
	v_exp_f32_e32 v80, v16
	v_exp_f32_e32 v81, v17
	v_exp_f32_e32 v98, v2
	v_exp_f32_e32 v82, v18
	v_exp_f32_e32 v99, v3
	v_exp_f32_e32 v83, v19
	v_exp_f32_e32 v100, v4
	v_exp_f32_e32 v84, v20
	v_exp_f32_e32 v101, v5
	v_exp_f32_e32 v85, v21
	v_exp_f32_e32 v102, v6
	v_exp_f32_e32 v86, v22
	v_exp_f32_e32 v103, v7
	v_exp_f32_e32 v87, v23
	v_exp_f32_e32 v104, v8
	v_exp_f32_e32 v88, v24
	v_exp_f32_e32 v105, v9
	v_exp_f32_e32 v89, v25
	v_exp_f32_e32 v106, v10
	v_exp_f32_e32 v90, v26
	v_exp_f32_e32 v107, v11
	v_exp_f32_e32 v91, v27
	v_exp_f32_e32 v108, v12
	v_exp_f32_e32 v92, v28
	v_exp_f32_e32 v109, v13
	v_exp_f32_e32 v93, v29
	v_exp_f32_e32 v110, v14
	v_exp_f32_e32 v94, v30
	v_exp_f32_e32 v111, v15
	v_exp_f32_e32 v95, v31
	v_and_b32_e32 v36, 32, v36
	v_lshlrev_b32_e32 v37, 4, v34
	s_waitcnt vmcnt(3) lgkmcnt(0)
	s_barrier
	v_add3_u32 v35, 0, v36, v35
	v_lshlrev_b32_e32 v36, 8, v214
	v_and_b32_e32 v37, 0xc0, v37
	v_and_b32_e32 v0, 3, v34
	s_mov_b32 s35, 1
	v_add3_u32 v239, v35, v36, v37
	s_mov_b32 s37, 0
	s_mov_b32 s15, 0
	s_cmp_lt_i32 s2, 1
	v_lshlrev_b32_e32 v210, 4, v0
	s_cbranch_scc1 .LBB0_314
	s_add_i32 s11, s25, -5
	s_lshl_b64 s[26:27], s[54:55], 1
	s_add_u32 s14, s12, s26
	s_addc_u32 s24, s13, s27
	s_add_u32 s26, s14, s31
	v_mov_b32_e32 v211, v213
	s_addc_u32 s27, s24, s29
	v_lshl_add_u64 v[0:1], s[26:27], 0, v[210:211]
	v_lshl_add_u64 v[0:1], v[0:1], 0, v[212:213]
	v_mov_b32_e32 v64, 0
	v_lshl_add_u64 v[66:67], s[6:7], 0, v[0:1]
	s_movk_i32 s28, 0x4000
	s_movk_i32 s27, 0x2000
	s_mov_b64 s[56:57], 0
	v_mov_b32_e32 v0, 0
	v_mov_b32_e32 v1, v64
	v_mov_b32_e32 v2, v64
	v_mov_b32_e32 v3, v64
	v_mov_b32_e32 v4, v64
	v_mov_b32_e32 v5, v64
	v_mov_b32_e32 v6, v64
	v_mov_b32_e32 v7, v64
	v_mov_b32_e32 v8, v64
	v_mov_b32_e32 v9, v64
	v_mov_b32_e32 v10, v64
	v_mov_b32_e32 v11, v64
	v_mov_b32_e32 v12, v64
	v_mov_b32_e32 v13, v64
	v_mov_b32_e32 v14, v64
	v_mov_b32_e32 v15, v64
	v_mov_b32_e32 v16, 0
	v_mov_b32_e32 v17, v64
	v_mov_b32_e32 v18, v64
	v_mov_b32_e32 v19, v64
	v_mov_b32_e32 v20, v64
	v_mov_b32_e32 v21, v64
	v_mov_b32_e32 v22, v64
	v_mov_b32_e32 v23, v64
	v_mov_b32_e32 v24, v64
	v_mov_b32_e32 v25, v64
	v_mov_b32_e32 v26, v64
	v_mov_b32_e32 v27, v64
	v_mov_b32_e32 v28, v64
	v_mov_b32_e32 v29, v64
	v_mov_b32_e32 v30, v64
	v_mov_b32_e32 v31, v64
	v_mov_b32_e32 v32, 0
	v_mov_b32_e32 v33, v64
	v_mov_b32_e32 v34, v64
	v_mov_b32_e32 v35, v64
	v_mov_b32_e32 v36, v64
	v_mov_b32_e32 v37, v64
	v_mov_b32_e32 v38, v64
	v_mov_b32_e32 v39, v64
	v_mov_b32_e32 v40, v64
	v_mov_b32_e32 v41, v64
	v_mov_b32_e32 v42, v64
	v_mov_b32_e32 v43, v64
	v_mov_b32_e32 v44, v64
	v_mov_b32_e32 v45, v64
	v_mov_b32_e32 v46, v64
	v_mov_b32_e32 v47, v64
	v_mov_b32_e32 v48, 0
	v_mov_b32_e32 v49, v64
	v_mov_b32_e32 v50, v64
	v_mov_b32_e32 v51, v64
	v_mov_b32_e32 v52, v64
	v_mov_b32_e32 v53, v64
	v_mov_b32_e32 v54, v64
	v_mov_b32_e32 v55, v64
	v_mov_b32_e32 v56, v64
	v_mov_b32_e32 v57, v64
	v_mov_b32_e32 v58, v64
	v_mov_b32_e32 v59, v64
	v_mov_b32_e32 v60, v64
	v_mov_b32_e32 v61, v64
	v_mov_b32_e32 v62, v64
	v_mov_b32_e32 v63, v64
	v_readfirstlane_b32 s98, v208
	v_readfirstlane_b32 s99, v209
	v_readfirstlane_b32 s100, v66
	v_readfirstlane_b32 s101, v67
	v_subrev_u32_e32 v250, s98, v208
	v_subrev_u32_e32 v251, s100, v66
	s_add_u32 s98, s98, 0x180000
	s_addc_u32 s99, s99, 0
	s_add_u32 s100, s100, 0x100c1000
	s_addc_u32 s101, s101, 0
.LBB0_304:
	s_mov_b32 s37, s28
	s_mov_b32 s14, s27
	v_lshl_add_u32 v65, s15, 1, v239
	ds_read_b64_tr_b16 v[72:73], v65 offset:24576
	ds_read_b64_tr_b16 v[74:75], v65 offset:25088
	v_add_f32_e32 v68, v96, v97
	v_add_f32_e32 v68, v98, v68
	v_add_f32_e32 v68, v99, v68
	v_add_f32_e32 v68, v100, v68
	v_add_f32_e32 v68, v101, v68
	v_cvt_pk_bf16_f32 v172, v96, v97
	v_cvt_pk_bf16_f32 v173, v98, v99
	s_waitcnt lgkmcnt(9)
	v_mfma_f32_32x32x16_bf16 v[128:143], v[204:207], v[168:171], 0
	ds_read_b64_tr_b16 v[76:77], v65 offset:28672
	ds_read_b64_tr_b16 v[78:79], v65 offset:29184
	v_add_f32_e32 v68, v102, v68
	v_add_f32_e32 v68, v103, v68
	v_add_f32_e32 v68, v104, v68
	v_add_f32_e32 v68, v105, v68
	v_cvt_pk_bf16_f32 v174, v100, v101
	v_cvt_pk_bf16_f32 v175, v102, v103
	s_waitcnt lgkmcnt(10)
	v_mfma_f32_32x32x16_bf16 v[112:127], v[200:203], v[168:171], 0
	ds_read_b64_tr_b16 v[96:97], v65 offset:32768
	ds_read_b64_tr_b16 v[98:99], v65 offset:33280
	v_add_f32_e32 v68, v106, v68
	v_add_f32_e32 v68, v107, v68
	v_add_f32_e32 v68, v108, v68
	v_add_f32_e32 v68, v109, v68
	v_cvt_pk_bf16_f32 v164, v104, v105
	v_cvt_pk_bf16_f32 v165, v106, v107
	s_waitcnt lgkmcnt(11)
	v_mfma_f32_32x32x16_bf16 v[128:143], v[196:199], v[160:163], v[128:143]
	ds_read_b64_tr_b16 v[100:101], v65 offset:36864
	ds_read_b64_tr_b16 v[102:103], v65 offset:37376
	v_add_f32_e32 v68, v110, v68
	v_add_f32_e32 v68, v111, v68
	v_add_f32_e32 v68, v80, v68
	v_add_f32_e32 v68, v81, v68
	v_cvt_pk_bf16_f32 v166, v108, v109
	v_cvt_pk_bf16_f32 v167, v110, v111
	s_waitcnt lgkmcnt(12)
	v_mfma_f32_32x32x16_bf16 v[112:127], v[192:195], v[160:163], v[112:127]
	ds_read_b64_tr_b16 v[104:105], v65 offset:25600
	ds_read_b64_tr_b16 v[106:107], v65 offset:26112
	v_add_f32_e32 v68, v82, v68
	v_add_f32_e32 v68, v83, v68
	v_add_f32_e32 v68, v84, v68
	v_add_f32_e32 v68, v85, v68
	v_cvt_pk_bf16_f32 v156, v80, v81
	v_cvt_pk_bf16_f32 v157, v82, v83
	s_waitcnt lgkmcnt(13)
	v_mfma_f32_32x32x16_bf16 v[128:143], v[188:191], v[152:155], v[128:143]
	ds_read_b64_tr_b16 v[80:81], v65 offset:29696
	ds_read_b64_tr_b16 v[82:83], v65 offset:30208
	v_add_f32_e32 v68, v86, v68
	v_add_f32_e32 v68, v87, v68
	v_add_f32_e32 v68, v88, v68
	v_add_f32_e32 v68, v89, v68
	v_cvt_pk_bf16_f32 v158, v84, v85
	v_cvt_pk_bf16_f32 v159, v86, v87
	s_waitcnt lgkmcnt(14)
	v_mfma_f32_32x32x16_bf16 v[112:127], v[184:187], v[152:155], v[112:127]
	ds_read_b64_tr_b16 v[84:85], v65 offset:33792
	ds_read_b64_tr_b16 v[86:87], v65 offset:34304
	v_add_f32_e32 v68, v90, v68
	v_add_f32_e32 v68, v91, v68
	v_add_f32_e32 v68, v92, v68
	v_add_f32_e32 v68, v93, v68
	v_cvt_pk_bf16_f32 v148, v88, v89
	v_cvt_pk_bf16_f32 v149, v90, v91
	s_waitcnt lgkmcnt(14)
	v_mfma_f32_32x32x16_bf16 v[128:143], v[180:183], v[144:147], v[128:143]
	ds_read_b64_tr_b16 v[88:89], v65 offset:37888
	ds_read_b64_tr_b16 v[90:91], v65 offset:38400
	v_add_f32_e32 v68, v94, v68
	v_add_f32_e32 v68, v95, v68
	v_cvt_pk_bf16_f32 v150, v92, v93
	v_cvt_pk_bf16_f32 v151, v94, v95
	v_mfma_f32_32x32x16_bf16 v[112:127], v[176:179], v[144:147], v[112:127]
	v_add_f32_e32 v64, v64, v68
	s_waitcnt lgkmcnt(14)
	v_mfma_f32_32x32x16_bf16 v[48:63], v[172:175], v[72:75], v[48:63]
	v_exp_f32_e32 v128, v128
	v_exp_f32_e32 v129, v129
	ds_read_b64_tr_b16 v[72:73], v65 offset:26624
	ds_read_b64_tr_b16 v[74:75], v65 offset:27136
	s_waitcnt lgkmcnt(14)
	v_mfma_f32_32x32x16_bf16 v[32:47], v[172:175], v[76:79], v[32:47]
	v_exp_f32_e32 v130, v130
	v_exp_f32_e32 v131, v131
	ds_read_b64_tr_b16 v[76:77], v65 offset:30720
	ds_read_b64_tr_b16 v[78:79], v65 offset:31232
	s_add_i32 s15, s27, s20
	s_mov_b32 m0, s15
	s_nop 0
	global_load_lds_dwordx4 v250, s[98:99]
	s_add_u32 s98, s98, 0x60000
	s_addc_u32 s99, s99, 0
	s_waitcnt lgkmcnt(14)
	v_mfma_f32_32x32x16_bf16 v[16:31], v[172:175], v[96:99], v[16:31]
	v_exp_f32_e32 v132, v132
	v_exp_f32_e32 v133, v133
	ds_read_b64_tr_b16 v[92:93], v65 offset:34816
	ds_read_b64_tr_b16 v[94:95], v65 offset:35328
	s_waitcnt lgkmcnt(14)
	v_mfma_f32_32x32x16_bf16 v[0:15], v[172:175], v[100:103], v[0:15]
	v_exp_f32_e32 v134, v134
	v_exp_f32_e32 v135, v135
	ds_read_b64_tr_b16 v[96:97], v65 offset:38912
	ds_read_b64_tr_b16 v[98:99], v65 offset:39424
	s_waitcnt lgkmcnt(14)
	v_mfma_f32_32x32x16_bf16 v[48:63], v[164:167], v[104:107], v[48:63]
	v_exp_f32_e32 v136, v136
	v_exp_f32_e32 v137, v137
	ds_read_b64_tr_b16 v[100:101], v65 offset:27648
	ds_read_b64_tr_b16 v[102:103], v65 offset:28160
	s_lshl_b32 s15, s28, 1
	s_add_i32 s15, s15, s21
	s_mov_b32 m0, s15
	s_nop 0
	global_load_lds_dwordx4 v251, s[100:101]
	s_waitcnt lgkmcnt(14)
	v_mfma_f32_32x32x16_bf16 v[32:47], v[164:167], v[80:83], v[32:47]
	v_exp_f32_e32 v138, v138
	v_exp_f32_e32 v139, v139
	ds_read_b64_tr_b16 v[80:81], v65 offset:31744
	ds_read_b64_tr_b16 v[82:83], v65 offset:32256
	s_waitcnt lgkmcnt(14)
	v_mfma_f32_32x32x16_bf16 v[16:31], v[164:167], v[84:87], v[16:31]
	v_exp_f32_e32 v140, v140
	v_exp_f32_e32 v141, v141
	ds_read_b64_tr_b16 v[84:85], v65 offset:35840
	ds_read_b64_tr_b16 v[86:87], v65 offset:36352
	s_waitcnt lgkmcnt(14)
	v_mfma_f32_32x32x16_bf16 v[0:15], v[164:167], v[88:91], v[0:15]
	v_exp_f32_e32 v142, v142
	v_exp_f32_e32 v143, v143
	ds_read_b64_tr_b16 v[88:89], v65 offset:39936
	ds_read_b64_tr_b16 v[90:91], v65 offset:40448
	s_lshl_b32 s15, s28, 1
	s_add_i32 s15, s15, s21
	s_addk_i32 s15, 0x1f80
	s_mov_b32 m0, s15
	s_nop 0
	global_load_lds_dwordx4 v251, s[100:101] offset:128
	s_add_u32 s100, s100, 0x60000
	s_addc_u32 s101, s101, 0
	s_waitcnt lgkmcnt(14)
	v_mfma_f32_32x32x16_bf16 v[48:63], v[156:159], v[72:75], v[48:63]
	v_exp_f32_e32 v112, v112
	v_exp_f32_e32 v113, v113
	s_waitcnt lgkmcnt(12)
	v_mfma_f32_32x32x16_bf16 v[32:47], v[156:159], v[76:79], v[32:47]
	v_exp_f32_e32 v114, v114
	v_exp_f32_e32 v115, v115
	v_add_u32_e32 v65, s37, v241
	ds_read_b128 v[72:75], v65
	ds_read_b128 v[76:79], v65 offset:512
	s_waitcnt lgkmcnt(12)
	v_mfma_f32_32x32x16_bf16 v[16:31], v[156:159], v[92:95], v[16:31]
	v_exp_f32_e32 v116, v116
	v_exp_f32_e32 v117, v117
	ds_read_b128 v[176:179], v65 offset:2048
	ds_read_b128 v[180:183], v65 offset:2560
	s_waitcnt lgkmcnt(12)
	v_mfma_f32_32x32x16_bf16 v[0:15], v[156:159], v[96:99], v[0:15]
	v_exp_f32_e32 v118, v118
	v_exp_f32_e32 v119, v119
	ds_read_b128 v[184:187], v65 offset:4096
	ds_read_b128 v[188:191], v65 offset:4608
	s_waitcnt lgkmcnt(12)
	v_mfma_f32_32x32x16_bf16 v[48:63], v[148:151], v[100:103], v[48:63]
	v_exp_f32_e32 v120, v120
	v_exp_f32_e32 v121, v121
	ds_read_b128 v[192:195], v65 offset:6144
	ds_read_b128 v[196:199], v65 offset:6656
	s_waitcnt lgkmcnt(12)
	v_mfma_f32_32x32x16_bf16 v[32:47], v[148:151], v[80:83], v[32:47]
	v_exp_f32_e32 v122, v122
	v_exp_f32_e32 v123, v123
	s_waitcnt lgkmcnt(10)
	v_mfma_f32_32x32x16_bf16 v[16:31], v[148:151], v[84:87], v[16:31]
	v_exp_f32_e32 v124, v124
	v_exp_f32_e32 v125, v125
	s_waitcnt lgkmcnt(8)
	v_mfma_f32_32x32x16_bf16 v[0:15], v[148:151], v[88:91], v[0:15]
	v_exp_f32_e32 v126, v126
	v_exp_f32_e32 v127, v127
	s_waitcnt vmcnt(3) lgkmcnt(0)
	s_barrier
	s_add_i32 s15, s28, 0x2000
	s_cmpk_lg_i32 s28, 0x4000
	s_cselect_b32 s27, s15, 0
	v_lshl_add_u32 v65, s14, 1, v239
	ds_read_b64_tr_b16 v[200:201], v65 offset:24576
	ds_read_b64_tr_b16 v[202:203], v65 offset:25088
	s_waitcnt lgkmcnt(9)
	v_mfma_f32_32x32x16_bf16 v[96:111], v[72:75], v[168:171], 0
	v_add_f32_e32 v80, v128, v129
	v_add_f32_e32 v80, v130, v80
	v_add_f32_e32 v80, v131, v80
	v_add_f32_e32 v80, v132, v80
	v_add_f32_e32 v80, v133, v80
	v_cvt_pk_bf16_f32 v172, v128, v129
	v_cvt_pk_bf16_f32 v173, v130, v131
	ds_read_b64_tr_b16 v[72:73], v65 offset:28672
	ds_read_b64_tr_b16 v[74:75], v65 offset:29184
	v_add_f32_e32 v80, v134, v80
	v_add_f32_e32 v80, v135, v80
	v_add_f32_e32 v80, v136, v80
	v_add_f32_e32 v128, v137, v80
	s_waitcnt lgkmcnt(10)
	v_mfma_f32_32x32x16_bf16 v[80:95], v[76:79], v[168:171], 0
	v_cvt_pk_bf16_f32 v174, v132, v133
	v_cvt_pk_bf16_f32 v175, v134, v135
	ds_read_b64_tr_b16 v[76:77], v65 offset:32768
	ds_read_b64_tr_b16 v[78:79], v65 offset:33280
	s_waitcnt lgkmcnt(11)
	v_mfma_f32_32x32x16_bf16 v[96:111], v[176:179], v[160:163], v[96:111]
	v_add_f32_e32 v128, v138, v128
	v_add_f32_e32 v128, v139, v128
	v_add_f32_e32 v128, v140, v128
	v_add_f32_e32 v132, v141, v128
	v_cvt_pk_bf16_f32 v164, v136, v137
	v_cvt_pk_bf16_f32 v165, v138, v139
	ds_read_b64_tr_b16 v[128:129], v65 offset:36864
	ds_read_b64_tr_b16 v[130:131], v65 offset:37376
	s_waitcnt lgkmcnt(12)
	v_mfma_f32_32x32x16_bf16 v[80:95], v[180:183], v[160:163], v[80:95]
	v_add_f32_e32 v132, v142, v132
	v_add_f32_e32 v132, v143, v132
	v_add_f32_e32 v132, v112, v132
	v_add_f32_e32 v136, v113, v132
	v_cvt_pk_bf16_f32 v166, v140, v141
	v_cvt_pk_bf16_f32 v167, v142, v143
	ds_read_b64_tr_b16 v[132:133], v65 offset:25600
	ds_read_b64_tr_b16 v[134:135], v65 offset:26112
	s_waitcnt lgkmcnt(13)
	v_mfma_f32_32x32x16_bf16 v[96:111], v[184:187], v[152:155], v[96:111]
	v_add_f32_e32 v136, v114, v136
	v_add_f32_e32 v136, v115, v136
	v_add_f32_e32 v136, v116, v136
	v_add_f32_e32 v136, v117, v136
	v_cvt_pk_bf16_f32 v156, v112, v113
	v_cvt_pk_bf16_f32 v157, v114, v115
	ds_read_b64_tr_b16 v[112:113], v65 offset:29696
	ds_read_b64_tr_b16 v[114:115], v65 offset:30208
	s_waitcnt lgkmcnt(14)
	v_mfma_f32_32x32x16_bf16 v[80:95], v[188:191], v[152:155], v[80:95]
	v_add_f32_e32 v136, v118, v136
	v_add_f32_e32 v136, v119, v136
	v_add_f32_e32 v136, v120, v136
	v_add_f32_e32 v136, v121, v136
	v_cvt_pk_bf16_f32 v158, v116, v117
	v_cvt_pk_bf16_f32 v159, v118, v119
	ds_read_b64_tr_b16 v[116:117], v65 offset:33792
	ds_read_b64_tr_b16 v[118:119], v65 offset:34304
	s_waitcnt lgkmcnt(14)
	v_mfma_f32_32x32x16_bf16 v[96:111], v[192:195], v[144:147], v[96:111]
	v_add_f32_e32 v136, v122, v136
	v_add_f32_e32 v136, v123, v136
	v_add_f32_e32 v136, v124, v136
	v_add_f32_e32 v136, v125, v136
	v_cvt_pk_bf16_f32 v148, v120, v121
	v_cvt_pk_bf16_f32 v149, v122, v123
	ds_read_b64_tr_b16 v[120:121], v65 offset:37888
	ds_read_b64_tr_b16 v[122:123], v65 offset:38400
	v_mfma_f32_32x32x16_bf16 v[80:95], v[196:199], v[144:147], v[80:95]
	v_add_f32_e32 v136, v126, v136
	v_add_f32_e32 v136, v127, v136
	v_cvt_pk_bf16_f32 v150, v124, v125
	v_cvt_pk_bf16_f32 v151, v126, v127
	v_add_f32_e32 v64, v64, v136
	s_add_i32 s35, s35, 2
	s_waitcnt lgkmcnt(14)
	v_mfma_f32_32x32x16_bf16 v[48:63], v[172:175], v[200:203], v[48:63]
	v_exp_f32_e32 v96, v96
	v_exp_f32_e32 v97, v97
	ds_read_b64_tr_b16 v[68:69], v65 offset:26624
	ds_read_b64_tr_b16 v[70:71], v65 offset:27136
	s_waitcnt lgkmcnt(14)
	v_mfma_f32_32x32x16_bf16 v[32:47], v[172:175], v[72:75], v[32:47]
	v_exp_f32_e32 v98, v98
	v_exp_f32_e32 v99, v99
	ds_read_b64_tr_b16 v[72:73], v65 offset:30720
	ds_read_b64_tr_b16 v[74:75], v65 offset:31232
	s_add_i32 s24, s28, s20
	s_mov_b32 m0, s24
	s_nop 0
	global_load_lds_dwordx4 v250, s[98:99]
	s_add_u32 s98, s98, 0x60000
	s_addc_u32 s99, s99, 0
	s_waitcnt lgkmcnt(14)
; #define WAIT_BAR(N) asm volatile("s_waitcnt vmcnt(" #N ") lgkmcnt(0)\n\ts_barrier":::"memory")
;   #define ROT() do{sl_prev=sl_cur;sl_cur=sl_next;sl_next=(sl_next==(NSLOT-1)*SLOTB)?0:sl_next+SLOTB;}while(0)
; template<int DUMMY> __device__ __forceinline__ void attn_pass2(const bf16*Qh,const bf16*__restrict__ Kh,const bf16*__restrict__ Vh,const int q0,char*shm,f32x16 (&o)[4]){
;     ...
;   int t=1;
;     ...
;   for(;t+5<NT;t+=2){
;     STEP(pB0,pB1,pA0,pA1,t,true,true,true);     WAIT_BAR(3); ROT();
;     STEP(pA0,pA1,pB0,pB1,t+1,true,true,true);   WAIT_BAR(3); ROT();
	v_mfma_f32_32x32x16_bf16 v[16:31], v[172:175], v[76:79], v[16:31]
	v_exp_f32_e32 v100, v100
	v_exp_f32_e32 v101, v101
	ds_read_b64_tr_b16 v[76:77], v65 offset:34816
	ds_read_b64_tr_b16 v[78:79], v65 offset:35328
	s_waitcnt lgkmcnt(14)
	v_mfma_f32_32x32x16_bf16 v[0:15], v[172:175], v[128:131], v[0:15]
	v_exp_f32_e32 v102, v102
	v_exp_f32_e32 v103, v103
	ds_read_b64_tr_b16 v[124:125], v65 offset:38912
	ds_read_b64_tr_b16 v[126:127], v65 offset:39424
	s_waitcnt lgkmcnt(14)
	v_mfma_f32_32x32x16_bf16 v[48:63], v[164:167], v[132:135], v[48:63]
	v_exp_f32_e32 v104, v104
	v_exp_f32_e32 v105, v105
	ds_read_b64_tr_b16 v[128:129], v65 offset:27648
	ds_read_b64_tr_b16 v[130:131], v65 offset:28160
	s_lshl_b32 s24, s27, 1
	s_add_i32 s24, s24, s21
	s_mov_b32 m0, s24
	s_nop 0
	global_load_lds_dwordx4 v251, s[100:101]
	s_waitcnt lgkmcnt(14)
	v_mfma_f32_32x32x16_bf16 v[32:47], v[164:167], v[112:115], v[32:47]
	v_exp_f32_e32 v106, v106
	v_exp_f32_e32 v107, v107
	ds_read_b64_tr_b16 v[112:113], v65 offset:31744
	ds_read_b64_tr_b16 v[114:115], v65 offset:32256
	s_waitcnt lgkmcnt(14)
	v_mfma_f32_32x32x16_bf16 v[16:31], v[164:167], v[116:119], v[16:31]
	v_exp_f32_e32 v108, v108
	v_exp_f32_e32 v109, v109
	ds_read_b64_tr_b16 v[116:117], v65 offset:35840
	ds_read_b64_tr_b16 v[118:119], v65 offset:36352
	s_waitcnt lgkmcnt(14)
	v_mfma_f32_32x32x16_bf16 v[0:15], v[164:167], v[120:123], v[0:15]
	v_exp_f32_e32 v110, v110
	v_exp_f32_e32 v111, v111
	ds_read_b64_tr_b16 v[120:121], v65 offset:39936
	ds_read_b64_tr_b16 v[122:123], v65 offset:40448
	s_lshl_b32 s24, s27, 1
	s_add_i32 s24, s24, s21
	s_addk_i32 s24, 0x1f80
	s_mov_b32 m0, s24
	s_nop 0
	global_load_lds_dwordx4 v251, s[100:101] offset:128
	s_add_u32 s100, s100, 0x60000
	s_addc_u32 s101, s101, 0
	s_waitcnt lgkmcnt(14)
	v_mfma_f32_32x32x16_bf16 v[48:63], v[156:159], v[68:71], v[48:63]
	v_exp_f32_e32 v80, v80
	v_exp_f32_e32 v81, v81
	s_waitcnt lgkmcnt(12)
	v_mfma_f32_32x32x16_bf16 v[32:47], v[156:159], v[72:75], v[32:47]
	v_exp_f32_e32 v82, v82
	v_exp_f32_e32 v83, v83
	v_add_u32_e32 v65, s27, v241
	ds_read_b128 v[204:207], v65
	ds_read_b128 v[200:203], v65 offset:512
	s_waitcnt lgkmcnt(12)
	v_mfma_f32_32x32x16_bf16 v[16:31], v[156:159], v[76:79], v[16:31]
	v_exp_f32_e32 v84, v84
	v_exp_f32_e32 v85, v85
	ds_read_b128 v[196:199], v65 offset:2048
	ds_read_b128 v[192:195], v65 offset:2560
	s_waitcnt lgkmcnt(12)
	v_mfma_f32_32x32x16_bf16 v[0:15], v[156:159], v[124:127], v[0:15]
	v_exp_f32_e32 v86, v86
	v_exp_f32_e32 v87, v87
	ds_read_b128 v[188:191], v65 offset:4096
	ds_read_b128 v[184:187], v65 offset:4608
	s_waitcnt lgkmcnt(12)
	v_mfma_f32_32x32x16_bf16 v[48:63], v[148:151], v[128:131], v[48:63]
	v_exp_f32_e32 v88, v88
	v_exp_f32_e32 v89, v89
	ds_read_b128 v[180:183], v65 offset:6144
	ds_read_b128 v[176:179], v65 offset:6656
	s_waitcnt lgkmcnt(12)
	v_mfma_f32_32x32x16_bf16 v[32:47], v[148:151], v[112:115], v[32:47]
	v_exp_f32_e32 v90, v90
	v_exp_f32_e32 v91, v91
	s_waitcnt lgkmcnt(10)
	v_mfma_f32_32x32x16_bf16 v[16:31], v[148:151], v[116:119], v[16:31]
	v_exp_f32_e32 v92, v92
	v_exp_f32_e32 v93, v93
	s_waitcnt lgkmcnt(8)
	v_mfma_f32_32x32x16_bf16 v[0:15], v[148:151], v[120:123], v[0:15]
	v_exp_f32_e32 v94, v94
	v_exp_f32_e32 v95, v95
	s_add_i32 s14, s27, 0x2000
	s_cmpk_lg_i32 s27, 0x4000
	s_waitcnt vmcnt(3) lgkmcnt(0)
	s_barrier
	s_cselect_b32 s28, s14, 0
	s_add_u32 s56, s56, 0xc0000
	s_addc_u32 s57, s57, 0
	s_cmp_ge_i32 s35, s11
	s_mov_b32 s15, s37
	s_cbranch_scc0 .LBB0_304
	s_ashr_i32 s11, s10, 31
	s_add_i32 s14, s35, 1
	s_cmp_lt_i32 s14, s25
	s_cbranch_scc1 .LBB0_315

; __global__ void __launch_bounds__(NWAVES * 64, 2) fwd_kernel(Args a_) {
	.amdhsa_kernel _Z10fwd_kernel4Args
		.amdhsa_group_segment_fixed_size 0
		.amdhsa_private_segment_fixed_size 0
		.amdhsa_kernarg_size 480
		.amdhsa_user_sgpr_count 2
		.amdhsa_user_sgpr_dispatch_ptr 0
		.amdhsa_user_sgpr_queue_ptr 0
		.amdhsa_user_sgpr_kernarg_segment_ptr 1
		.amdhsa_user_sgpr_dispatch_id 0
		.amdhsa_user_sgpr_kernarg_preload_length 0
		.amdhsa_user_sgpr_kernarg_preload_offset 0
		.amdhsa_user_sgpr_private_segment_size 0
		.amdhsa_uses_dynamic_stack 0
		.amdhsa_enable_private_segment 0
		.amdhsa_system_sgpr_workgroup_id_x 1
		.amdhsa_system_sgpr_workgroup_id_y 0
		.amdhsa_system_sgpr_workgroup_id_z 0
		.amdhsa_system_sgpr_workgroup_info 0
		.amdhsa_system_vgpr_workitem_id 2
		.amdhsa_next_free_vgpr 256
		.amdhsa_next_free_sgpr 102
		.amdhsa_accum_offset 256
		.amdhsa_reserve_vcc 1
		.amdhsa_float_round_mode_32 0
		.amdhsa_float_round_mode_16_64 0
		.amdhsa_float_denorm_mode_32 3
		.amdhsa_float_denorm_mode_16_64 3
		.amdhsa_dx10_clamp 1
		.amdhsa_ieee_mode 1
		.amdhsa_fp16_overflow 0
		.amdhsa_tg_split 0
		.amdhsa_exception_fp_ieee_invalid_op 0
		.amdhsa_exception_fp_denorm_src 0
		.amdhsa_exception_fp_ieee_div_zero 0
		.amdhsa_exception_fp_ieee_overflow 0
		.amdhsa_exception_fp_ieee_underflow 0
		.amdhsa_exception_fp_ieee_inexact 0
		.amdhsa_exception_int_div_zero 0
	.end_amdhsa_kernel

; __global__ void __launch_bounds__(NWAVES * 64, 2) fwd_kernel(Args a_) {
amdhsa.kernels:
  - .agpr_count:     0
    .args:
      - .offset:         0
        .size:           224
        .value_kind:     by_value
      - .offset:         224
        .size:           4
        .value_kind:     hidden_block_count_x
      - .offset:         228
        .size:           4
        .value_kind:     hidden_block_count_y
      - .offset:         232
        .size:           4
        .value_kind:     hidden_block_count_z
      - .offset:         236
        .size:           2
        .value_kind:     hidden_group_size_x
      - .offset:         238
        .size:           2
        .value_kind:     hidden_group_size_y
      - .offset:         240
        .size:           2
        .value_kind:     hidden_group_size_z
      - .offset:         242
        .size:           2
        .value_kind:     hidden_remainder_x
      - .offset:         244
        .size:           2
        .value_kind:     hidden_remainder_y
      - .offset:         246
        .size:           2
        .value_kind:     hidden_remainder_z
      - .offset:         264
        .size:           8
        .value_kind:     hidden_global_offset_x
      - .offset:         272
        .size:           8
        .value_kind:     hidden_global_offset_y
      - .offset:         280
        .size:           8
        .value_kind:     hidden_global_offset_z
      - .offset:         288
        .size:           2
        .value_kind:     hidden_grid_dims
      - .offset:         312
        .size:           8
        .value_kind:     hidden_multigrid_sync_arg
      - .offset:         344
        .size:           4
        .value_kind:     hidden_dynamic_lds_size
    .group_segment_fixed_size: 0
    .kernarg_segment_align: 8
    .kernarg_segment_size: 480
    .language:       OpenCL C
    .language_version:
      - 2
      - 0
    .max_flat_workgroup_size: 512
    .name:           _Z10fwd_kernel4Args
    .private_segment_fixed_size: 0
    .sgpr_count:     108
    .sgpr_spill_count: 28
    .symbol:         _Z10fwd_kernel4Args.kd
    .uniform_work_group_size: 1
    .uses_dynamic_stack: false
    .vgpr_count:     256
    .vgpr_spill_count: 0
    .wavefront_size: 64
